# out-proj epilogue: residual (read-once) row loads carry the nt hint
# speedup vs baseline: 1.0012x; 1.0012x over previous
.LBB0_461:
	v_cndmask_b32_e64 v64, 0, 1, s[42:43]
	s_and_b64 vcc, exec, s[8:9]
	v_cmp_ne_u32_e64 s[8:9], 1, v64
	s_cbranch_vccz .LBB0_410
	v_lshl_add_u64 v[64:65], v[98:99], 2, s[68:69]
	v_add_co_u32_e32 v66, vcc, 0x10000, v64
	v_add_u32_e32 v100, s12, v110
	s_nop 0
	v_addc_co_u32_e32 v67, vcc, 0, v65, vcc
	global_load_dwordx4 v[92:95], v[64:65], off nt
	global_load_dwordx4 v[88:91], v[66:67], off nt
	v_add_co_u32_e32 v66, vcc, 0x20000, v64
	s_nop 1
	v_addc_co_u32_e32 v67, vcc, 0, v65, vcc
	v_add_co_u32_e32 v68, vcc, 0x30000, v64
	s_nop 1
	v_addc_co_u32_e32 v69, vcc, 0, v65, vcc
	global_load_dwordx4 v[84:87], v[66:67], off nt
	global_load_dwordx4 v[80:83], v[68:69], off nt
	v_add_co_u32_e32 v66, vcc, 0x40000, v64
	s_nop 1
	v_addc_co_u32_e32 v67, vcc, 0, v65, vcc
	v_add_co_u32_e32 v68, vcc, 0x50000, v64
	s_nop 1
	v_addc_co_u32_e32 v69, vcc, 0, v65, vcc
	global_load_dwordx4 v[76:79], v[66:67], off nt
	global_load_dwordx4 v[72:75], v[68:69], off nt
	v_add_co_u32_e32 v66, vcc, 0x60000, v64
	s_nop 1
	v_addc_co_u32_e32 v67, vcc, 0, v65, vcc
	v_add_co_u32_e32 v64, vcc, 0x70000, v64
	s_nop 1
	v_addc_co_u32_e32 v65, vcc, 0, v65, vcc
	global_load_dwordx4 v[68:71], v[66:67], off nt
	s_nop 0
	global_load_dwordx4 v[64:67], v[64:65], off nt
	ds_read_b128 v[102:105], v100
	s_and_b64 vcc, exec, s[8:9]
	s_waitcnt vmcnt(7) lgkmcnt(0)
	v_pk_add_f32 v[94:95], v[94:95], v[104:105]
	v_pk_add_f32 v[92:93], v[92:93], v[102:103]
	s_cbranch_vccnz .LBB0_464
	v_lshlrev_b32_e32 v101, 2, v98
	buffer_store_dwordx4 v[92:95], v101, s[16:19], 0 offen sc1

.LBB0_578:
	s_and_b64 vcc, exec, s[10:11]
	s_cbranch_vccz .LBB0_527
	v_lshl_add_u64 v[0:1], v[34:35], 2, s[68:69]
	v_add_co_u32_e32 v2, vcc, 0x10000, v0
	v_add_u32_e32 v36, s42, v110
	s_nop 0
	v_addc_co_u32_e32 v3, vcc, 0, v1, vcc
	global_load_dwordx4 v[28:31], v[0:1], off nt
	global_load_dwordx4 v[24:27], v[2:3], off nt
	v_add_co_u32_e32 v2, vcc, 0x20000, v0
	s_nop 1
	v_addc_co_u32_e32 v3, vcc, 0, v1, vcc
	v_add_co_u32_e32 v4, vcc, 0x30000, v0
	s_nop 1
	v_addc_co_u32_e32 v5, vcc, 0, v1, vcc
	global_load_dwordx4 v[20:23], v[2:3], off nt
	global_load_dwordx4 v[16:19], v[4:5], off nt
	v_add_co_u32_e32 v2, vcc, 0x40000, v0
	s_nop 1
	v_addc_co_u32_e32 v3, vcc, 0, v1, vcc
	v_add_co_u32_e32 v4, vcc, 0x50000, v0
	s_nop 1
	v_addc_co_u32_e32 v5, vcc, 0, v1, vcc
	global_load_dwordx4 v[12:15], v[2:3], off nt
	global_load_dwordx4 v[8:11], v[4:5], off nt
	v_add_co_u32_e32 v2, vcc, 0x60000, v0
	s_nop 1
	v_addc_co_u32_e32 v3, vcc, 0, v1, vcc
	v_add_co_u32_e32 v0, vcc, 0x70000, v0
	s_nop 1
	v_addc_co_u32_e32 v1, vcc, 0, v1, vcc
	global_load_dwordx4 v[4:7], v[2:3], off nt
	s_nop 0
	global_load_dwordx4 v[0:3], v[0:1], off nt
	ds_read_b128 v[38:41], v36
	s_and_b64 vcc, exec, s[8:9]
	s_waitcnt vmcnt(7) lgkmcnt(0)
	v_pk_add_f32 v[30:31], v[30:31], v[40:41]
	v_pk_add_f32 v[28:29], v[28:29], v[38:39]
	s_cbranch_vccnz .LBB0_581
	v_lshlrev_b32_e32 v37, 2, v34
	buffer_store_dwordx4 v[28:31], v37, s[16:19], 0 offen sc1
